# GEMM unit headers no longer drain all VMEM (stores and K-tile prefetch stay in flight across units)
# baseline (speedup 1.0000x reference)
; template <class Epi, class Sched, bool ALIGN_EPI = false, bool SP2 = false>
; __device__ __forceinline__ void gemm_phase(PG8_LAS unsigned char* lds, const Gemm g, const Sched& S, const Epi& E) {
;     ...
;         const bool has_next = S.next(ui + 1, nxt);
;         const char* nA = has_next ? (const char*)g.A + (size_t)nxt.pm * tstep : cA; const char* nB = has_next ? (const char*)g.Bt + (size_t)nxt.pn * tstep : cB;
;     ...
;         if (!has_next) break;
; #pragma unroll
;         for (int a = 0; a < 2; ++a)
; #pragma unroll
;             for (int b = 0; b < 2; ++b)
; #pragma unroll
;                 for (int m = 0; m < 4; ++m)
; #pragma unroll
;                     for (int n = 0; n < 2; ++n) acc[a][b][m][n] = (f32x4){0.f, 0.f, 0.f, 0.f};
;         cur = nxt; cA = nA; cB = nB; ++ui;
.LBB0_127:
	s_ashr_i32 s13, s12, 31
	s_lshl_b64 s[14:15], s[12:13], 19
	s_add_u32 s14, s28, s14
	s_addc_u32 s15, s29, s15
	s_and_b64 s[20:21], s[4:5], exec
	s_cselect_b32 s13, s15, s1
	s_cselect_b32 s36, s14, s0
	s_ashr_i32 s11, s10, 31
	s_lshl_b64 s[20:21], s[10:11], 19
	s_add_u32 s20, s16, s20
	s_addc_u32 s21, s19, s21
	s_and_b64 s[38:39], s[4:5], exec
	s_cselect_b32 s11, s21, s23
	s_cselect_b32 s37, s20, s22
	s_add_u32 s0, s0, 0x40080
	v_lshl_add_u32 v144, s24, 8, v152
	s_addc_u32 s1, s1, 0
	v_ashrrev_i32_e32 v145, 31, v144
	s_add_u32 s38, s22, 0x100
	v_lshl_add_u64 v[146:147], v[144:145], 2, s[72:73]
	s_addc_u32 s39, s23, 0
	s_mov_b32 s40, -2
	s_nop 0
	s_branch .LBB0_129

; template <class Epi, class Sched, bool ALIGN_EPI = false, bool SP2 = false>
; __device__ __forceinline__ void gemm_phase(PG8_LAS unsigned char* lds, const Gemm g, const Sched& S, const Epi& E) {
;     ...
;         const bool has_next = S.next(ui + 1, nxt);
;         const char* nA = has_next ? (const char*)g.A + (size_t)nxt.pm * tstep : cA; const char* nB = has_next ? (const char*)g.Bt + (size_t)nxt.pn * tstep : cB;
;     ...
;         if (!has_next) break;
; #pragma unroll
;         for (int a = 0; a < 2; ++a)
; #pragma unroll
;             for (int b = 0; b < 2; ++b)
; #pragma unroll
;                 for (int m = 0; m < 4; ++m)
; #pragma unroll
;                     for (int n = 0; n < 2; ++n) acc[a][b][m][n] = (f32x4){0.f, 0.f, 0.f, 0.f};
;         cur = nxt; cA = nA; cB = nB; ++ui;
.LBB0_954:
	s_ashr_i32 s25, s24, 31
	s_lshl_b64 s[38:39], s[24:25], 19
	s_add_u32 s96, s60, s38
	s_addc_u32 s97, s67, s39
	s_and_b64 s[38:39], s[8:9], exec
	s_cselect_b32 s25, s97, s11
	s_cselect_b32 s37, s96, s10
	s_ashr_i32 s23, s22, 31
	s_lshl_b64 s[38:39], s[22:23], 19
	s_add_u32 s78, s16, s38
	s_addc_u32 s79, s19, s39
	s_and_b64 s[38:39], s[8:9], exec
	s_cselect_b32 s23, s79, s5
	s_cselect_b32 s38, s78, s4
	s_add_u32 s10, s10, 0x40080
	s_addc_u32 s11, s11, 0
	s_add_u32 s39, s4, 0x100
	s_addc_u32 s40, s5, 0
	s_mov_b32 s41, -2
	s_waitcnt lgkmcnt(0)
	s_nop 0
	s_branch .LBB0_955

; template <class Epi, class Sched, bool ALIGN_EPI = false, bool SP2 = false>
; __device__ __forceinline__ void gemm_phase(PG8_LAS unsigned char* lds, const Gemm g, const Sched& S, const Epi& E) {
;     ...
;         const bool has_next = S.next(ui + 1, nxt);
;         const char* nA = has_next ? (const char*)g.A + (size_t)nxt.pm * tstep : cA; const char* nB = has_next ? (const char*)g.Bt + (size_t)nxt.pn * tstep : cB;
;     ...
;         if (!has_next) break;
; #pragma unroll
;         for (int a = 0; a < 2; ++a)
; #pragma unroll
;             for (int b = 0; b < 2; ++b)
; #pragma unroll
;                 for (int m = 0; m < 4; ++m)
; #pragma unroll
;                     for (int n = 0; n < 2; ++n) acc[a][b][m][n] = (f32x4){0.f, 0.f, 0.f, 0.f};
;         cur = nxt; cA = nA; cB = nB; ++ui;
.LBB0_1102:
	s_ashr_i32 s13, s12, 31
	s_lshl_b64 s[14:15], s[12:13], 19
	s_add_u32 s14, s74, s14
	s_addc_u32 s15, s75, s15
	s_and_b64 s[20:21], s[6:7], exec
	s_cselect_b32 s13, s15, s5
	s_cselect_b32 s36, s14, s4
	s_ashr_i32 s11, s10, 31
	s_lshl_b64 s[20:21], s[10:11], 19
	s_add_u32 s20, s16, s20
	s_addc_u32 s21, s78, s21
	s_and_b64 s[38:39], s[6:7], exec
	s_cselect_b32 s11, s21, s23
	s_cselect_b32 s37, s20, s22
	s_add_u32 s4, s4, 0x40080
	v_lshl_add_u32 v144, s24, 8, v152
	s_addc_u32 s5, s5, 0
	v_ashrrev_i32_e32 v145, 31, v144
	s_add_u32 s38, s22, 0x100
	v_lshl_add_u64 v[146:147], v[144:145], 2, s[52:53]
	s_addc_u32 s39, s23, 0
	s_mov_b32 s40, -2
	s_nop 0
	s_branch .LBB0_1104

; template <class Epi, class Sched, bool ALIGN_EPI = false, bool SP2 = false>
; __device__ __forceinline__ void gemm_phase(PG8_LAS unsigned char* lds, const Gemm g, const Sched& S, const Epi& E) {
;     ...
;         if (!has_next) break;
; #pragma unroll
;         for (int a = 0; a < 2; ++a)
; #pragma unroll
;             for (int b = 0; b < 2; ++b)
; #pragma unroll
;                 for (int m = 0; m < 4; ++m)
; #pragma unroll
;                     for (int n = 0; n < 2; ++n) acc[a][b][m][n] = (f32x4){0.f, 0.f, 0.f, 0.f};
;         cur = nxt; cA = nA; cB = nB; ++ui;
.LBB0_1180:
	s_add_u32 s38, s10, 0x100
	s_addc_u32 s39, s11, 0
	s_mov_b32 s40, -2
	s_waitcnt lgkmcnt(0)
	s_nop 0
	s_branch .LBB0_1181
